# v45 full stack plus s_setprio toggles removed from the K=256 per-layer-embedding GEMM loop as well
# baseline (speedup 1.0000x reference)
; #define PG8_STAGE(bufoff, gbase, voff) do { _Pragma("unroll") for (int _i = 0; _i < 2; ++_i) \
;         __builtin_amdgcn_global_load_lds((const unsigned*)((const char*)(gbase) + (voff)[_i]), (PG8_LAS unsigned*)(lds + (bufoff) + ldsw + _i * 8192), 16, 0, 0); } while (0)
; #define PG8_LDA(dst, b, h) do { _Pragma("unroll") for (int m = 0; m < 4; ++m) _Pragma("unroll") for (int k = 0; k < 2; ++k) dst[m][k] = *(const PG8_LAS bf16x8*)(lds + PG8_SA(b, h) + aoff + m * 2048 + k * 1024); } while (0)
; #define PG8_LDB(dst, b, h) do { _Pragma("unroll") for (int n = 0; n < 2; ++n) _Pragma("unroll") for (int k = 0; k < 2; ++k) dst[n][k] = *(const PG8_LAS bf16x8*)(lds + PG8_SB(b, h) + boff + n * 2048 + k * 1024); } while (0)
; #define PG8_WAIT_V(n) asm volatile("s_waitcnt vmcnt(" #n ")" ::: "memory")
; #define PG8_WAIT_L(n) asm volatile("s_waitcnt lgkmcnt(" #n ")" ::: "memory")
; #define PG8_BAR __builtin_amdgcn_s_barrier()
; #define PG8_SCHED __builtin_amdgcn_sched_barrier(0)
; template <class Epi, class Sched, bool ALIGN_EPI = false, bool SP2 = false>
; __device__ __forceinline__ void gemm_phase(PG8_LAS unsigned char* lds, const Gemm g, const Sched& S, const Epi& E) {
;     ...
;         const bool has_next = S.next(ui + 1, nxt);
;         const char* nA = has_next ? (const char*)g.A + (size_t)nxt.pm * tstepA : cA; const char* nB = has_next ? (const char*)g.Bt + (size_t)nxt.pn * tstepB : cB;
;         for (int t = 0; t < nt; t += 2) {
;             const bool last = (t == nt - 2);
;             const char* a1 = cA + (size_t)(t + 1) * kstep;
;             const char* a2 = last ? nA : cA + (size_t)(t + 2) * kstep; const char* b2 = last ? nB : cB + (size_t)(t + 2) * kstep;
;             const char* a3 = a2 + kstep; const char* b3 = b2 + kstep;
;             if (last && has_next) S.a_ready(nxt);
;             if constexpr (SP2) {
;             PG8_LDB(B0, 0, 0); PG8_LDB(B1, 0, 1); PG8_SCHED; PG8_LDA(At, 0, 0); PG8_STAGE(PG8_SA(1, 1), a1 + hstepA, voffA);
;             PG8_WAIT_V(8); PG8_WAIT_L(0); PG8_BAR; PG8_MMA(0, 0, At, B0); PG8_MMA(0, 1, At, B1); PG8_BAR; PG8_SCHED;
;             PG8_LDA(At, 0, 1); PG8_STAGE(PG8_SB(0, 0), b2, voffB); PG8_STAGE(PG8_SB(0, 1), b2 + hstepB, voffB); PG8_STAGE(PG8_SA(0, 0), a2, voffA);
;             PG8_WAIT_V(8); PG8_WAIT_L(0); PG8_BAR; PG8_MMA(1, 0, At, B0); PG8_MMA(1, 1, At, B1); PG8_BAR; PG8_SCHED;
.LBB0_671:
	s_ashr_i32 s15, s14, 31
	s_lshl_b64 s[2:3], s[14:15], 17
	v_readlane_b32 s13, v254, 4
	s_add_u32 s16, s13, s2
	v_readlane_b32 s2, v254, 6
	s_addc_u32 s17, s2, s3
	s_and_b64 s[2:3], s[0:1], exec
	s_cselect_b32 s85, s17, s87
	s_cselect_b32 s84, s16, s86
	s_ashr_i32 s13, s12, 31
	s_lshl_b64 s[2:3], s[12:13], 17
	v_readlane_b32 s13, v254, 8
	s_add_u32 s66, s13, s2
	v_readlane_b32 s2, v254, 10
	s_addc_u32 s67, s2, s3
	s_and_b64 s[2:3], s[0:1], exec
	s_cselect_b32 s83, s67, s89
	s_cselect_b32 s82, s66, s88
	s_add_i32 s80, 0, 0x10000
	s_add_i32 s13, 0, 0x14000
	v_add_u32_e32 v194, s80, v136
	v_add_u32_e32 v195, s13, v136
	ds_read_b128 v[0:3], v194
	ds_read_b128 v[4:7], v194 offset:1024
	ds_read_b128 v[8:11], v194 offset:2048
	ds_read_b128 v[12:15], v194 offset:3072
	ds_read_b128 v[16:19], v195
	ds_read_b128 v[20:23], v195 offset:1024
	ds_read_b128 v[24:27], v195 offset:2048
	ds_read_b128 v[28:31], v195 offset:3072
	v_mov_b32_e32 v252, 0x358637bd
	v_mov_b64_e32 v[242:243], 0x200
	s_add_u32 s2, s86, 0x10080
	s_addc_u32 s3, s87, 0
	s_add_i32 s91, s20, 0xc000
	s_waitcnt vmcnt(0)
	v_lshl_add_u64 v[64:65], s[2:3], 0, v[132:133]
	s_mov_b32 m0, s91
	ds_read_b128 v[32:35], v137
	ds_read_b128 v[36:39], v137 offset:1024
	ds_read_b128 v[40:43], v137 offset:2048
	ds_read_b128 v[44:47], v137 offset:3072
	ds_read_b128 v[48:51], v137 offset:4096
	ds_read_b128 v[52:55], v137 offset:5120
	ds_read_b128 v[56:59], v137 offset:6144
	ds_read_b128 v[60:63], v137 offset:7168
	global_load_lds_dwordx4 v[64:65], off
	v_lshl_add_u64 v[64:65], s[2:3], 0, v[130:131]
	s_add_i32 s2, s20, 0xe000
	s_mov_b32 m0, s2
	s_nop 0
	global_load_lds_dwordx4 v[64:65], off
	s_waitcnt vmcnt(8)
	s_waitcnt lgkmcnt(0)
	s_barrier
	s_waitcnt lgkmcnt(0)
	v_mfma_f32_16x16x32_bf16 v[64:67], v[0:3], v[32:35], 0
	v_mfma_f32_16x16x32_bf16 v[68:71], v[8:11], v[32:35], 0
	v_mfma_f32_16x16x32_bf16 v[72:75], v[0:3], v[40:43], 0
	v_mfma_f32_16x16x32_bf16 v[76:79], v[8:11], v[40:43], 0
	v_mfma_f32_16x16x32_bf16 v[80:83], v[0:3], v[48:51], 0
	v_mfma_f32_16x16x32_bf16 v[84:87], v[8:11], v[48:51], 0
	v_mfma_f32_16x16x32_bf16 v[88:91], v[0:3], v[56:59], 0
	v_mfma_f32_16x16x32_bf16 v[92:95], v[8:11], v[56:59], 0
	v_mfma_f32_16x16x32_bf16 v[64:67], v[4:7], v[36:39], v[64:67]
	v_mfma_f32_16x16x32_bf16 v[68:71], v[12:15], v[36:39], v[68:71]
	v_mfma_f32_16x16x32_bf16 v[72:75], v[4:7], v[44:47], v[72:75]
	v_mfma_f32_16x16x32_bf16 v[76:79], v[12:15], v[44:47], v[76:79]
	v_mfma_f32_16x16x32_bf16 v[80:83], v[4:7], v[52:55], v[80:83]
	v_mfma_f32_16x16x32_bf16 v[84:87], v[12:15], v[52:55], v[84:87]
	v_mfma_f32_16x16x32_bf16 v[88:91], v[4:7], v[60:63], v[88:91]
	v_mfma_f32_16x16x32_bf16 v[92:95], v[12:15], v[60:63], v[92:95]
	v_mfma_f32_16x16x32_bf16 v[96:99], v[16:19], v[32:35], 0
	v_mfma_f32_16x16x32_bf16 v[32:35], v[24:27], v[32:35], 0
	v_mfma_f32_16x16x32_bf16 v[96:99], v[20:23], v[36:39], v[96:99]
	v_mfma_f32_16x16x32_bf16 v[32:35], v[28:31], v[36:39], v[32:35]
	v_mfma_f32_16x16x32_bf16 v[36:39], v[16:19], v[40:43], 0
	v_mfma_f32_16x16x32_bf16 v[40:43], v[24:27], v[40:43], 0
	v_mfma_f32_16x16x32_bf16 v[36:39], v[20:23], v[44:47], v[36:39]
	v_mfma_f32_16x16x32_bf16 v[40:43], v[28:31], v[44:47], v[40:43]
	v_mfma_f32_16x16x32_bf16 v[44:47], v[16:19], v[48:51], 0
	v_mfma_f32_16x16x32_bf16 v[48:51], v[24:27], v[48:51], 0
	v_mfma_f32_16x16x32_bf16 v[44:47], v[20:23], v[52:55], v[44:47]
	v_mfma_f32_16x16x32_bf16 v[48:51], v[28:31], v[52:55], v[48:51]
	v_mfma_f32_16x16x32_bf16 v[52:55], v[16:19], v[56:59], 0
	v_mfma_f32_16x16x32_bf16 v[56:59], v[24:27], v[56:59], 0
	v_mfma_f32_16x16x32_bf16 v[52:55], v[20:23], v[60:63], v[52:55]
	v_mfma_f32_16x16x32_bf16 v[56:59], v[28:31], v[60:63], v[56:59]
	s_barrier
	s_add_i32 s80, s80, s19
	v_lshl_add_u64 v[134:135], s[88:89], 0, v[192:193]
	s_mov_b64 s[92:93], 0x100
	s_add_i32 s3, s80, 0x2000
	v_lshl_add_u64 v[138:139], v[134:135], 0, s[92:93]
	s_mov_b32 m0, s80
	v_lshl_add_u64 v[190:191], s[88:89], 0, v[128:129]
	s_add_u32 s30, s88, 0x10100
	ds_read_b128 v[60:63], v137 offset:16384
	ds_read_b128 v[100:103], v137 offset:17408
	ds_read_b128 v[104:107], v137 offset:18432
	ds_read_b128 v[108:111], v137 offset:19456
	ds_read_b128 v[112:115], v137 offset:20480
	ds_read_b128 v[116:119], v137 offset:21504
	ds_read_b128 v[120:123], v137 offset:22528
	ds_read_b128 v[124:127], v137 offset:23552
	global_load_lds_dwordx4 v[138:139], off
	v_lshl_add_u64 v[138:139], v[190:191], 0, s[92:93]
	s_mov_b32 m0, s3
	s_addc_u32 s31, s89, 0
	s_add_i32 s13, s13, s19
	global_load_lds_dwordx4 v[138:139], off
	v_lshl_add_u64 v[138:139], s[30:31], 0, v[192:193]
	s_mov_b32 m0, s13
	s_add_i32 s15, s13, 0x2000
	global_load_lds_dwordx4 v[138:139], off
	v_lshl_add_u64 v[138:139], s[30:31], 0, v[128:129]
	s_mov_b32 m0, s15
	v_lshl_add_u64 v[210:211], s[86:87], 0, v[132:133]
	global_load_lds_dwordx4 v[138:139], off
	v_lshl_add_u64 v[138:139], v[210:211], 0, s[92:93]
	s_mov_b32 m0, s20
	v_lshl_add_u64 v[212:213], s[86:87], 0, v[130:131]
	global_load_lds_dwordx4 v[138:139], off
	v_lshl_add_u64 v[138:139], v[212:213], 0, s[92:93]
	s_mov_b32 m0, s21
	s_nop 0
	global_load_lds_dwordx4 v[138:139], off
	s_waitcnt vmcnt(8)
	s_waitcnt lgkmcnt(0)
	s_barrier
; #define PG8_STAGE(bufoff, gbase, voff) do { _Pragma("unroll") for (int _i = 0; _i < 2; ++_i) \
;         __builtin_amdgcn_global_load_lds((const unsigned*)((const char*)(gbase) + (voff)[_i]), (PG8_LAS unsigned*)(lds + (bufoff) + ldsw + _i * 8192), 16, 0, 0); } while (0)
; #define PG8_LDA(dst, b, h) do { _Pragma("unroll") for (int m = 0; m < 4; ++m) _Pragma("unroll") for (int k = 0; k < 2; ++k) dst[m][k] = *(const PG8_LAS bf16x8*)(lds + PG8_SA(b, h) + aoff + m * 2048 + k * 1024); } while (0)
; #define PG8_LDB(dst, b, h) do { _Pragma("unroll") for (int n = 0; n < 2; ++n) _Pragma("unroll") for (int k = 0; k < 2; ++k) dst[n][k] = *(const PG8_LAS bf16x8*)(lds + PG8_SB(b, h) + boff + n * 2048 + k * 1024); } while (0)
; #define PG8_MMA(ai, bj, At, Bt) do { __builtin_amdgcn_s_setprio(1); _Pragma("unroll") for (int m = 0; m < 4; ++m) _Pragma("unroll") for (int n = 0; n < 2; ++n) _Pragma("unroll") for (int k = 0; k < 2; ++k) \
;         acc[ai][bj][m][n] = __builtin_amdgcn_mfma_f32_16x16x32_bf16(Bt[n][k], At[m][k], acc[ai][bj][m][n], 0, 0, 0); __builtin_amdgcn_s_setprio(0); } while (0)
; #define PG8_WAIT_V(n) asm volatile("s_waitcnt vmcnt(" #n ")" ::: "memory")
; #define PG8_WAIT_L(n) asm volatile("s_waitcnt lgkmcnt(" #n ")" ::: "memory")
; #define PG8_BAR __builtin_amdgcn_s_barrier()
; #define PG8_SCHED __builtin_amdgcn_sched_barrier(0)
; template <class Epi, class Sched, bool ALIGN_EPI = false, bool SP2 = false>
; __device__ __forceinline__ void gemm_phase(PG8_LAS unsigned char* lds, const Gemm g, const Sched& S, const Epi& E) {
;     ...
;             PG8_WAIT_V(8); PG8_WAIT_L(0); PG8_BAR; PG8_MMA(1, 0, At, B0); PG8_MMA(1, 1, At, B1); PG8_BAR; PG8_SCHED;
;             PG8_LDB(B0, 1, 0); PG8_LDB(B1, 1, 1); PG8_SCHED; PG8_LDA(At, 1, 0); PG8_STAGE(PG8_SA(0, 1), a2 + hstepA, voffA);
;             PG8_WAIT_V(8); PG8_WAIT_L(0); PG8_BAR; PG8_MMA(0, 0, At, B0); PG8_MMA(0, 1, At, B1); PG8_BAR; PG8_SCHED;
	s_waitcnt lgkmcnt(0)
	v_mfma_f32_16x16x32_bf16 v[138:141], v[0:3], v[60:63], 0
	v_mfma_f32_16x16x32_bf16 v[146:149], v[0:3], v[104:107], 0
	v_mfma_f32_16x16x32_bf16 v[154:157], v[0:3], v[112:115], 0
	v_mfma_f32_16x16x32_bf16 v[0:3], v[0:3], v[120:123], 0
	v_mfma_f32_16x16x32_bf16 v[138:141], v[4:7], v[100:103], v[138:141]
	v_mfma_f32_16x16x32_bf16 v[146:149], v[4:7], v[108:111], v[146:149]
	v_mfma_f32_16x16x32_bf16 v[154:157], v[4:7], v[116:119], v[154:157]
	v_mfma_f32_16x16x32_bf16 v[0:3], v[4:7], v[124:127], v[0:3]
	v_mfma_f32_16x16x32_bf16 v[4:7], v[8:11], v[120:123], 0
	v_mfma_f32_16x16x32_bf16 v[142:145], v[8:11], v[60:63], 0
	v_mfma_f32_16x16x32_bf16 v[150:153], v[8:11], v[104:107], 0
	v_mfma_f32_16x16x32_bf16 v[158:161], v[8:11], v[112:115], 0
	v_mfma_f32_16x16x32_bf16 v[4:7], v[12:15], v[124:127], v[4:7]
	v_mfma_f32_16x16x32_bf16 v[142:145], v[12:15], v[100:103], v[142:145]
	v_mfma_f32_16x16x32_bf16 v[150:153], v[12:15], v[108:111], v[150:153]
	v_mfma_f32_16x16x32_bf16 v[158:161], v[12:15], v[116:119], v[158:161]
	v_mfma_f32_16x16x32_bf16 v[8:11], v[16:19], v[60:63], 0
	v_mfma_f32_16x16x32_bf16 v[12:15], v[24:27], v[60:63], 0
	v_mfma_f32_16x16x32_bf16 v[8:11], v[20:23], v[100:103], v[8:11]
	v_mfma_f32_16x16x32_bf16 v[12:15], v[28:31], v[100:103], v[12:15]
	v_mfma_f32_16x16x32_bf16 v[60:63], v[16:19], v[104:107], 0
	v_mfma_f32_16x16x32_bf16 v[100:103], v[24:27], v[104:107], 0
	v_mfma_f32_16x16x32_bf16 v[104:107], v[16:19], v[112:115], 0
	v_mfma_f32_16x16x32_bf16 v[16:19], v[16:19], v[120:123], 0
	v_mfma_f32_16x16x32_bf16 v[60:63], v[20:23], v[108:111], v[60:63]
	v_mfma_f32_16x16x32_bf16 v[100:103], v[28:31], v[108:111], v[100:103]
	v_mfma_f32_16x16x32_bf16 v[104:107], v[20:23], v[116:119], v[104:107]
	v_mfma_f32_16x16x32_bf16 v[108:111], v[24:27], v[112:115], 0
	v_mfma_f32_16x16x32_bf16 v[16:19], v[20:23], v[124:127], v[16:19]
	v_mfma_f32_16x16x32_bf16 v[20:23], v[24:27], v[120:123], 0
	v_mfma_f32_16x16x32_bf16 v[108:111], v[28:31], v[116:119], v[108:111]
	v_mfma_f32_16x16x32_bf16 v[20:23], v[28:31], v[124:127], v[20:23]
	s_barrier
	s_add_i32 s92, 0, 0x18000
	s_add_i32 s77, 0, 0x1c000
	v_add_u32_e32 v218, s92, v136
	v_add_u32_e32 v226, s77, v136
	ds_read_b128 v[24:27], v218
	ds_read_b128 v[28:31], v218 offset:1024
	ds_read_b128 v[112:115], v218 offset:2048
	ds_read_b128 v[116:119], v218 offset:3072
	ds_read_b128 v[120:123], v226
	ds_read_b128 v[124:127], v226 offset:1024
	ds_read_b128 v[162:165], v226 offset:2048
	ds_read_b128 v[166:169], v226 offset:3072
	s_add_u32 s30, s86, 0x10100
	s_addc_u32 s31, s87, 0
	s_mov_b32 m0, s34
	v_lshl_add_u64 v[214:215], s[30:31], 0, v[132:133]
	ds_read_b128 v[170:173], v137 offset:32768
	ds_read_b128 v[174:177], v137 offset:33792
	ds_read_b128 v[178:181], v137 offset:34816
	ds_read_b128 v[182:185], v137 offset:35840
	ds_read_b128 v[186:189], v137 offset:36864
	ds_read_b128 v[198:201], v137 offset:37888
	ds_read_b128 v[202:205], v137 offset:38912
	ds_read_b128 v[206:209], v137 offset:39936
	global_load_lds_dwordx4 v[214:215], off
	v_lshl_add_u64 v[214:215], s[30:31], 0, v[130:131]
	s_mov_b32 m0, s45
	s_nop 0
	global_load_lds_dwordx4 v[214:215], off
	s_waitcnt vmcnt(8)
	s_waitcnt lgkmcnt(0)
	s_barrier
	s_waitcnt lgkmcnt(0)
	v_mfma_f32_16x16x32_bf16 v[64:67], v[24:27], v[170:173], v[64:67]
	v_mfma_f32_16x16x32_bf16 v[68:71], v[112:115], v[170:173], v[68:71]
	v_mfma_f32_16x16x32_bf16 v[72:75], v[24:27], v[178:181], v[72:75]
	v_mfma_f32_16x16x32_bf16 v[76:79], v[112:115], v[178:181], v[76:79]
	v_mfma_f32_16x16x32_bf16 v[80:83], v[24:27], v[186:189], v[80:83]
	v_mfma_f32_16x16x32_bf16 v[84:87], v[112:115], v[186:189], v[84:87]
	v_mfma_f32_16x16x32_bf16 v[88:91], v[24:27], v[202:205], v[88:91]
	v_mfma_f32_16x16x32_bf16 v[92:95], v[112:115], v[202:205], v[92:95]
	v_mfma_f32_16x16x32_bf16 v[64:67], v[28:31], v[174:177], v[64:67]
	v_mfma_f32_16x16x32_bf16 v[68:71], v[116:119], v[174:177], v[68:71]
	v_mfma_f32_16x16x32_bf16 v[72:75], v[28:31], v[182:185], v[72:75]
	v_mfma_f32_16x16x32_bf16 v[76:79], v[116:119], v[182:185], v[76:79]
	v_mfma_f32_16x16x32_bf16 v[80:83], v[28:31], v[198:201], v[80:83]
	v_mfma_f32_16x16x32_bf16 v[84:87], v[116:119], v[198:201], v[84:87]
	v_mfma_f32_16x16x32_bf16 v[88:91], v[28:31], v[206:209], v[88:91]
	v_mfma_f32_16x16x32_bf16 v[92:95], v[116:119], v[206:209], v[92:95]
	v_mfma_f32_16x16x32_bf16 v[96:99], v[120:123], v[170:173], v[96:99]
	v_mfma_f32_16x16x32_bf16 v[32:35], v[162:165], v[170:173], v[32:35]
	v_mfma_f32_16x16x32_bf16 v[36:39], v[120:123], v[178:181], v[36:39]
	v_mfma_f32_16x16x32_bf16 v[40:43], v[162:165], v[178:181], v[40:43]
	v_mfma_f32_16x16x32_bf16 v[44:47], v[120:123], v[186:189], v[44:47]
	v_mfma_f32_16x16x32_bf16 v[48:51], v[162:165], v[186:189], v[48:51]
	v_mfma_f32_16x16x32_bf16 v[52:55], v[120:123], v[202:205], v[52:55]
	v_mfma_f32_16x16x32_bf16 v[56:59], v[162:165], v[202:205], v[56:59]
	v_mfma_f32_16x16x32_bf16 v[96:99], v[124:127], v[174:177], v[96:99]
	v_mfma_f32_16x16x32_bf16 v[32:35], v[166:169], v[174:177], v[32:35]
	v_mfma_f32_16x16x32_bf16 v[36:39], v[124:127], v[182:185], v[36:39]
	v_mfma_f32_16x16x32_bf16 v[40:43], v[166:169], v[182:185], v[40:43]
	v_mfma_f32_16x16x32_bf16 v[44:47], v[124:127], v[198:201], v[44:47]
	v_mfma_f32_16x16x32_bf16 v[48:51], v[166:169], v[198:201], v[48:51]
	v_mfma_f32_16x16x32_bf16 v[52:55], v[124:127], v[206:209], v[52:55]
	v_mfma_f32_16x16x32_bf16 v[56:59], v[166:169], v[206:209], v[56:59]
	s_barrier
; #define PG8_STAGE(bufoff, gbase, voff) do { _Pragma("unroll") for (int _i = 0; _i < 2; ++_i) \
;         __builtin_amdgcn_global_load_lds((const unsigned*)((const char*)(gbase) + (voff)[_i]), (PG8_LAS unsigned*)(lds + (bufoff) + ldsw + _i * 8192), 16, 0, 0); } while (0)
; #define PG8_LDA(dst, b, h) do { _Pragma("unroll") for (int m = 0; m < 4; ++m) _Pragma("unroll") for (int k = 0; k < 2; ++k) dst[m][k] = *(const PG8_LAS bf16x8*)(lds + PG8_SA(b, h) + aoff + m * 2048 + k * 1024); } while (0)
; #define PG8_LDB(dst, b, h) do { _Pragma("unroll") for (int n = 0; n < 2; ++n) _Pragma("unroll") for (int k = 0; k < 2; ++k) dst[n][k] = *(const PG8_LAS bf16x8*)(lds + PG8_SB(b, h) + boff + n * 2048 + k * 1024); } while (0)
; #define PG8_MMA(ai, bj, At, Bt) do { __builtin_amdgcn_s_setprio(1); _Pragma("unroll") for (int m = 0; m < 4; ++m) _Pragma("unroll") for (int n = 0; n < 2; ++n) _Pragma("unroll") for (int k = 0; k < 2; ++k) \
;         acc[ai][bj][m][n] = __builtin_amdgcn_mfma_f32_16x16x32_bf16(Bt[n][k], At[m][k], acc[ai][bj][m][n], 0, 0, 0); __builtin_amdgcn_s_setprio(0); } while (0)
; #define PG8_WAIT_V(n) asm volatile("s_waitcnt vmcnt(" #n ")" ::: "memory")
; #define PG8_WAIT_L(n) asm volatile("s_waitcnt lgkmcnt(" #n ")" ::: "memory")
; #define PG8_BAR __builtin_amdgcn_s_barrier()
; #define PG8_SCHED __builtin_amdgcn_sched_barrier(0)
; template <class Epi, class Sched, bool ALIGN_EPI = false, bool SP2 = false>
; __device__ __forceinline__ void gemm_phase(PG8_LAS unsigned char* lds, const Gemm g, const Sched& S, const Epi& E) {
;     ...
;             PG8_LDB(B0, 0, 0); PG8_LDB(B1, 0, 1); PG8_SCHED; PG8_LDA(At, 0, 0); PG8_STAGE(PG8_SA(1, 1), a1 + hstepA, voffA);
;             PG8_WAIT_V(8); PG8_WAIT_L(0); PG8_BAR; PG8_MMA(0, 0, At, B0); PG8_MMA(0, 1, At, B1); PG8_BAR; PG8_SCHED;
;     ...
;             PG8_LDA(At, 1, 1); PG8_STAGE(PG8_SB(1, 0), b3, voffB); PG8_STAGE(PG8_SB(1, 1), b3 + hstepB, voffB); PG8_STAGE(PG8_SA(1, 0), a3, voffA);
;             PG8_WAIT_V(8); PG8_WAIT_L(0); PG8_BAR; PG8_MMA(1, 0, At, B0); PG8_MMA(1, 1, At, B1); PG8_BAR; PG8_SCHED;
	s_add_i32 s92, s92, s19
	s_mov_b64 s[94:95], 0x180
	s_add_i32 s90, s92, 0x2000
	v_lshl_add_u64 v[134:135], v[134:135], 0, s[94:95]
	s_mov_b32 m0, s92
	s_add_u32 s30, s88, 0x10180
	ds_read_b128 v[170:173], v137 offset:49152
	ds_read_b128 v[174:177], v137 offset:50176
	ds_read_b128 v[178:181], v137 offset:51200
	ds_read_b128 v[182:185], v137 offset:52224
	ds_read_b128 v[186:189], v137 offset:53248
	ds_read_b128 v[198:201], v137 offset:54272
	ds_read_b128 v[202:205], v137 offset:55296
	ds_read_b128 v[206:209], v137 offset:56320
	global_load_lds_dwordx4 v[134:135], off
	v_lshl_add_u64 v[134:135], v[190:191], 0, s[94:95]
	s_mov_b32 m0, s90
	s_addc_u32 s31, s89, 0
	s_add_i32 s88, s77, s19
	global_load_lds_dwordx4 v[134:135], off
	v_lshl_add_u64 v[134:135], s[30:31], 0, v[192:193]
	s_mov_b32 m0, s88
	s_add_i32 s89, s88, 0x2000
	global_load_lds_dwordx4 v[134:135], off
	v_lshl_add_u64 v[134:135], s[30:31], 0, v[128:129]
	s_mov_b32 m0, s89
	s_nop 0
	global_load_lds_dwordx4 v[134:135], off
	v_lshl_add_u64 v[134:135], v[210:211], 0, s[94:95]
	s_mov_b32 m0, s63
	s_nop 0
	global_load_lds_dwordx4 v[134:135], off
	v_lshl_add_u64 v[134:135], v[212:213], 0, s[94:95]
	s_mov_b32 m0, s64
	s_nop 0
	global_load_lds_dwordx4 v[134:135], off
	s_waitcnt vmcnt(8)
	s_waitcnt lgkmcnt(0)
	s_barrier
	s_waitcnt lgkmcnt(0)
	v_mfma_f32_16x16x32_bf16 v[0:3], v[24:27], v[202:205], v[0:3]
	v_mfma_f32_16x16x32_bf16 v[4:7], v[112:115], v[202:205], v[4:7]
	v_mfma_f32_16x16x32_bf16 v[138:141], v[24:27], v[170:173], v[138:141]
	v_mfma_f32_16x16x32_bf16 v[142:145], v[112:115], v[170:173], v[142:145]
	v_mfma_f32_16x16x32_bf16 v[146:149], v[24:27], v[178:181], v[146:149]
	v_mfma_f32_16x16x32_bf16 v[150:153], v[112:115], v[178:181], v[150:153]
	v_mfma_f32_16x16x32_bf16 v[154:157], v[24:27], v[186:189], v[154:157]
	v_mfma_f32_16x16x32_bf16 v[158:161], v[112:115], v[186:189], v[158:161]
	v_mfma_f32_16x16x32_bf16 v[0:3], v[28:31], v[206:209], v[0:3]
	v_mfma_f32_16x16x32_bf16 v[4:7], v[116:119], v[206:209], v[4:7]
	v_mfma_f32_16x16x32_bf16 v[138:141], v[28:31], v[174:177], v[138:141]
	v_mfma_f32_16x16x32_bf16 v[142:145], v[116:119], v[174:177], v[142:145]
	v_mfma_f32_16x16x32_bf16 v[146:149], v[28:31], v[182:185], v[146:149]
	v_mfma_f32_16x16x32_bf16 v[150:153], v[116:119], v[182:185], v[150:153]
	v_mfma_f32_16x16x32_bf16 v[154:157], v[28:31], v[198:201], v[154:157]
	v_mfma_f32_16x16x32_bf16 v[158:161], v[116:119], v[198:201], v[158:161]
	v_mfma_f32_16x16x32_bf16 v[8:11], v[120:123], v[170:173], v[8:11]
	v_mfma_f32_16x16x32_bf16 v[12:15], v[162:165], v[170:173], v[12:15]
	v_mfma_f32_16x16x32_bf16 v[24:27], v[120:123], v[178:181], v[60:63]
	v_mfma_f32_16x16x32_bf16 v[28:31], v[162:165], v[178:181], v[100:103]
	v_mfma_f32_16x16x32_bf16 v[60:63], v[120:123], v[186:189], v[104:107]
	v_mfma_f32_16x16x32_bf16 v[100:103], v[162:165], v[186:189], v[108:111]
	v_mfma_f32_16x16x32_bf16 v[16:19], v[120:123], v[202:205], v[16:19]
	v_mfma_f32_16x16x32_bf16 v[20:23], v[162:165], v[202:205], v[20:23]
	v_mfma_f32_16x16x32_bf16 v[8:11], v[124:127], v[174:177], v[8:11]
	v_mfma_f32_16x16x32_bf16 v[12:15], v[166:169], v[174:177], v[12:15]
	v_mfma_f32_16x16x32_bf16 v[24:27], v[124:127], v[182:185], v[24:27]
	v_mfma_f32_16x16x32_bf16 v[28:31], v[166:169], v[182:185], v[28:31]
	v_mfma_f32_16x16x32_bf16 v[60:63], v[124:127], v[198:201], v[60:63]
	v_mfma_f32_16x16x32_bf16 v[100:103], v[166:169], v[198:201], v[100:103]
	v_mfma_f32_16x16x32_bf16 v[16:19], v[124:127], v[206:209], v[16:19]
	v_mfma_f32_16x16x32_bf16 v[20:23], v[166:169], v[206:209], v[20:23]
	s_barrier
	ds_read_b128 v[104:107], v194
	ds_read_b128 v[108:111], v194 offset:1024
	ds_read_b128 v[112:115], v194 offset:2048
	ds_read_b128 v[116:119], v194 offset:3072
	ds_read_b128 v[120:123], v195
	ds_read_b128 v[124:127], v195 offset:1024
	ds_read_b128 v[162:165], v195 offset:2048
	ds_read_b128 v[166:169], v195 offset:3072
	s_add_u32 s30, s86, 0x10180
	s_addc_u32 s31, s87, 0
	s_mov_b32 m0, s91
	v_lshl_add_u64 v[134:135], s[30:31], 0, v[132:133]
	ds_read_b128 v[170:173], v137
	ds_read_b128 v[174:177], v137 offset:1024
	ds_read_b128 v[178:181], v137 offset:2048
	ds_read_b128 v[182:185], v137 offset:3072
	ds_read_b128 v[186:189], v137 offset:4096
	ds_read_b128 v[198:201], v137 offset:5120
	ds_read_b128 v[202:205], v137 offset:6144
	ds_read_b128 v[206:209], v137 offset:7168
	global_load_lds_dwordx4 v[134:135], off
	v_lshl_add_u64 v[134:135], s[30:31], 0, v[130:131]
	s_mov_b32 m0, s2
	s_nop 0
	global_load_lds_dwordx4 v[134:135], off
	s_waitcnt vmcnt(8)
	s_waitcnt lgkmcnt(0)
	s_barrier
; #define PG8_STAGE(bufoff, gbase, voff) do { _Pragma("unroll") for (int _i = 0; _i < 2; ++_i) \
;         __builtin_amdgcn_global_load_lds((const unsigned*)((const char*)(gbase) + (voff)[_i]), (PG8_LAS unsigned*)(lds + (bufoff) + ldsw + _i * 8192), 16, 0, 0); } while (0)
; #define PG8_LDA(dst, b, h) do { _Pragma("unroll") for (int m = 0; m < 4; ++m) _Pragma("unroll") for (int k = 0; k < 2; ++k) dst[m][k] = *(const PG8_LAS bf16x8*)(lds + PG8_SA(b, h) + aoff + m * 2048 + k * 1024); } while (0)
; #define PG8_MMA(ai, bj, At, Bt) do { __builtin_amdgcn_s_setprio(1); _Pragma("unroll") for (int m = 0; m < 4; ++m) _Pragma("unroll") for (int n = 0; n < 2; ++n) _Pragma("unroll") for (int k = 0; k < 2; ++k) \
;         acc[ai][bj][m][n] = __builtin_amdgcn_mfma_f32_16x16x32_bf16(Bt[n][k], At[m][k], acc[ai][bj][m][n], 0, 0, 0); __builtin_amdgcn_s_setprio(0); } while (0)
; #define PG8_WAIT_V(n) asm volatile("s_waitcnt vmcnt(" #n ")" ::: "memory")
; #define PG8_WAIT_L(n) asm volatile("s_waitcnt lgkmcnt(" #n ")" ::: "memory")
; #define PG8_BAR __builtin_amdgcn_s_barrier()
; #define PG8_SCHED __builtin_amdgcn_sched_barrier(0)
; template <class Epi, class Sched, bool ALIGN_EPI = false, bool SP2 = false>
; __device__ __forceinline__ void gemm_phase(PG8_LAS unsigned char* lds, const Gemm g, const Sched& S, const Epi& E) {
;     ...
;             PG8_WAIT_V(8); PG8_WAIT_L(0); PG8_BAR; PG8_MMA(0, 0, At, B0); PG8_MMA(0, 1, At, B1); PG8_BAR; PG8_SCHED;
;             PG8_LDA(At, 0, 1); PG8_STAGE(PG8_SB(0, 0), b2, voffB); PG8_STAGE(PG8_SB(0, 1), b2 + hstepB, voffB); PG8_STAGE(PG8_SA(0, 0), a2, voffA);
;             PG8_WAIT_V(8); PG8_WAIT_L(0); PG8_BAR; PG8_MMA(1, 0, At, B0); PG8_MMA(1, 1, At, B1); PG8_BAR; PG8_SCHED;
	s_waitcnt lgkmcnt(0)
	v_mfma_f32_16x16x32_bf16 v[64:67], v[104:107], v[170:173], v[64:67]
	v_mfma_f32_16x16x32_bf16 v[68:71], v[112:115], v[170:173], v[68:71]
	v_mfma_f32_16x16x32_bf16 v[72:75], v[104:107], v[178:181], v[72:75]
	v_mfma_f32_16x16x32_bf16 v[76:79], v[112:115], v[178:181], v[76:79]
	v_mfma_f32_16x16x32_bf16 v[80:83], v[104:107], v[186:189], v[80:83]
	v_mfma_f32_16x16x32_bf16 v[84:87], v[112:115], v[186:189], v[84:87]
	v_mfma_f32_16x16x32_bf16 v[88:91], v[104:107], v[202:205], v[88:91]
	v_mfma_f32_16x16x32_bf16 v[64:67], v[108:111], v[174:177], v[64:67]
	v_mfma_f32_16x16x32_bf16 v[68:71], v[116:119], v[174:177], v[68:71]
	v_mfma_f32_16x16x32_bf16 v[72:75], v[108:111], v[182:185], v[72:75]
	v_mfma_f32_16x16x32_bf16 v[76:79], v[116:119], v[182:185], v[76:79]
	v_mfma_f32_16x16x32_bf16 v[80:83], v[108:111], v[198:201], v[80:83]
	v_mfma_f32_16x16x32_bf16 v[84:87], v[116:119], v[198:201], v[84:87]
	v_mfma_f32_16x16x32_bf16 v[88:91], v[108:111], v[206:209], v[88:91]
	v_mfma_f32_16x16x32_bf16 v[92:95], v[112:115], v[202:205], v[92:95]
	v_mfma_f32_16x16x32_bf16 v[210:213], v[116:119], v[206:209], v[92:95]
	v_mfma_f32_16x16x32_bf16 v[92:95], v[120:123], v[170:173], v[96:99]
	v_mfma_f32_16x16x32_bf16 v[32:35], v[162:165], v[170:173], v[32:35]
	v_mfma_f32_16x16x32_bf16 v[36:39], v[120:123], v[178:181], v[36:39]
	v_mfma_f32_16x16x32_bf16 v[40:43], v[162:165], v[178:181], v[40:43]
	v_mfma_f32_16x16x32_bf16 v[44:47], v[120:123], v[186:189], v[44:47]
	v_mfma_f32_16x16x32_bf16 v[48:51], v[162:165], v[186:189], v[48:51]
	v_mfma_f32_16x16x32_bf16 v[52:55], v[120:123], v[202:205], v[52:55]
	v_mfma_f32_16x16x32_bf16 v[96:99], v[124:127], v[174:177], v[92:95]
	v_mfma_f32_16x16x32_bf16 v[32:35], v[166:169], v[174:177], v[32:35]
	v_mfma_f32_16x16x32_bf16 v[36:39], v[124:127], v[182:185], v[36:39]
	v_mfma_f32_16x16x32_bf16 v[40:43], v[166:169], v[182:185], v[40:43]
	v_mfma_f32_16x16x32_bf16 v[44:47], v[124:127], v[198:201], v[44:47]
	v_mfma_f32_16x16x32_bf16 v[48:51], v[166:169], v[198:201], v[48:51]
	v_mfma_f32_16x16x32_bf16 v[170:173], v[124:127], v[206:209], v[52:55]
	v_mfma_f32_16x16x32_bf16 v[52:55], v[162:165], v[202:205], v[56:59]
	v_mfma_f32_16x16x32_bf16 v[174:177], v[166:169], v[206:209], v[52:55]
	s_barrier
	s_mov_b32 m0, s80
	v_lshl_add_u64 v[134:135], s[82:83], 0, v[192:193]
	s_add_u32 s2, s82, 0x10000
	s_nop 1
	ds_read_b128 v[52:55], v137 offset:16384
	ds_read_b128 v[56:59], v137 offset:17408
	ds_read_b128 v[92:95], v137 offset:18432
	ds_read_b128 v[178:181], v137 offset:19456
	ds_read_b128 v[182:185], v137 offset:20480
	ds_read_b128 v[186:189], v137 offset:21504
	ds_read_b128 v[198:201], v137 offset:22528
	ds_read_b128 v[202:205], v137 offset:23552
	global_load_lds_dwordx4 v[134:135], off
	v_lshl_add_u64 v[190:191], s[82:83], 0, v[128:129]
	s_mov_b32 m0, s3
	s_addc_u32 s3, s83, 0
	global_load_lds_dwordx4 v[190:191], off
	v_lshl_add_u64 v[206:207], s[2:3], 0, v[192:193]
	s_mov_b32 m0, s13
	v_lshl_add_u64 v[194:195], s[84:85], 0, v[132:133]
	global_load_lds_dwordx4 v[206:207], off
	v_lshl_add_u64 v[206:207], s[2:3], 0, v[128:129]
	s_mov_b32 m0, s15
	v_lshl_add_u64 v[196:197], s[84:85], 0, v[130:131]
	global_load_lds_dwordx4 v[206:207], off
	s_mov_b32 m0, s20
	s_nop 0
	global_load_lds_dwordx4 v[194:195], off
	s_mov_b32 m0, s21
	s_nop 0
	global_load_lds_dwordx4 v[196:197], off
	s_waitcnt vmcnt(8)
	s_waitcnt lgkmcnt(0)
	s_barrier
	s_waitcnt lgkmcnt(0)
	v_mfma_f32_16x16x32_bf16 v[0:3], v[104:107], v[198:201], v[0:3]
	v_mfma_f32_16x16x32_bf16 v[4:7], v[112:115], v[198:201], v[4:7]
	v_mfma_f32_16x16x32_bf16 v[138:141], v[104:107], v[52:55], v[138:141]
	v_mfma_f32_16x16x32_bf16 v[142:145], v[112:115], v[52:55], v[142:145]
	v_mfma_f32_16x16x32_bf16 v[146:149], v[104:107], v[92:95], v[146:149]
	v_mfma_f32_16x16x32_bf16 v[150:153], v[112:115], v[92:95], v[150:153]
	v_mfma_f32_16x16x32_bf16 v[154:157], v[104:107], v[182:185], v[154:157]
	v_mfma_f32_16x16x32_bf16 v[158:161], v[112:115], v[182:185], v[158:161]
	v_mfma_f32_16x16x32_bf16 v[0:3], v[108:111], v[202:205], v[0:3]
	v_mfma_f32_16x16x32_bf16 v[4:7], v[116:119], v[202:205], v[4:7]
	v_mfma_f32_16x16x32_bf16 v[138:141], v[108:111], v[56:59], v[138:141]
	v_mfma_f32_16x16x32_bf16 v[142:145], v[116:119], v[56:59], v[142:145]
	v_mfma_f32_16x16x32_bf16 v[146:149], v[108:111], v[178:181], v[146:149]
	v_mfma_f32_16x16x32_bf16 v[150:153], v[116:119], v[178:181], v[150:153]
	v_mfma_f32_16x16x32_bf16 v[154:157], v[108:111], v[186:189], v[154:157]
	v_mfma_f32_16x16x32_bf16 v[158:161], v[116:119], v[186:189], v[158:161]
	v_mfma_f32_16x16x32_bf16 v[12:15], v[162:165], v[52:55], v[12:15]
	v_mfma_f32_16x16x32_bf16 v[206:209], v[166:169], v[56:59], v[12:15]
	v_mfma_f32_16x16x32_bf16 v[12:15], v[120:123], v[92:95], v[24:27]
	v_mfma_f32_16x16x32_bf16 v[24:27], v[124:127], v[178:181], v[12:15]
	v_mfma_f32_16x16x32_bf16 v[12:15], v[162:165], v[92:95], v[28:31]
	v_mfma_f32_16x16x32_bf16 v[178:181], v[166:169], v[178:181], v[12:15]
	v_mfma_f32_16x16x32_bf16 v[12:15], v[120:123], v[182:185], v[60:63]
	v_mfma_f32_16x16x32_bf16 v[214:217], v[124:127], v[186:189], v[12:15]
	v_mfma_f32_16x16x32_bf16 v[12:15], v[162:165], v[182:185], v[100:103]
	v_mfma_f32_16x16x32_bf16 v[8:11], v[120:123], v[52:55], v[8:11]
	v_mfma_f32_16x16x32_bf16 v[182:185], v[166:169], v[186:189], v[12:15]
	v_mfma_f32_16x16x32_bf16 v[12:15], v[120:123], v[198:201], v[16:19]
	v_mfma_f32_16x16x32_bf16 v[8:11], v[124:127], v[56:59], v[8:11]
	v_mfma_f32_16x16x32_bf16 v[186:189], v[124:127], v[202:205], v[12:15]
	v_mfma_f32_16x16x32_bf16 v[12:15], v[162:165], v[198:201], v[20:23]
	v_mfma_f32_16x16x32_bf16 v[162:165], v[166:169], v[202:205], v[12:15]
	s_barrier
; #define PG8_STAGE(bufoff, gbase, voff) do { _Pragma("unroll") for (int _i = 0; _i < 2; ++_i) \
;         __builtin_amdgcn_global_load_lds((const unsigned*)((const char*)(gbase) + (voff)[_i]), (PG8_LAS unsigned*)(lds + (bufoff) + ldsw + _i * 8192), 16, 0, 0); } while (0)
; #define PG8_LDA(dst, b, h) do { _Pragma("unroll") for (int m = 0; m < 4; ++m) _Pragma("unroll") for (int k = 0; k < 2; ++k) dst[m][k] = *(const PG8_LAS bf16x8*)(lds + PG8_SA(b, h) + aoff + m * 2048 + k * 1024); } while (0)
; #define PG8_LDB(dst, b, h) do { _Pragma("unroll") for (int n = 0; n < 2; ++n) _Pragma("unroll") for (int k = 0; k < 2; ++k) dst[n][k] = *(const PG8_LAS bf16x8*)(lds + PG8_SB(b, h) + boff + n * 2048 + k * 1024); } while (0)
; #define PG8_MMA(ai, bj, At, Bt) do { __builtin_amdgcn_s_setprio(1); _Pragma("unroll") for (int m = 0; m < 4; ++m) _Pragma("unroll") for (int n = 0; n < 2; ++n) _Pragma("unroll") for (int k = 0; k < 2; ++k) \
;         acc[ai][bj][m][n] = __builtin_amdgcn_mfma_f32_16x16x32_bf16(Bt[n][k], At[m][k], acc[ai][bj][m][n], 0, 0, 0); __builtin_amdgcn_s_setprio(0); } while (0)
; #define PG8_WAIT_V(n) asm volatile("s_waitcnt vmcnt(" #n ")" ::: "memory")
; #define PG8_WAIT_L(n) asm volatile("s_waitcnt lgkmcnt(" #n ")" ::: "memory")
; #define PG8_BAR __builtin_amdgcn_s_barrier()
; #define PG8_SCHED __builtin_amdgcn_sched_barrier(0)
; template <class Epi, class Sched, bool ALIGN_EPI = false, bool SP2 = false>
; __device__ __forceinline__ void gemm_phase(PG8_LAS unsigned char* lds, const Gemm g, const Sched& S, const Epi& E) {
;     ...
;             PG8_LDB(B0, 1, 0); PG8_LDB(B1, 1, 1); PG8_SCHED; PG8_LDA(At, 1, 0); PG8_STAGE(PG8_SA(0, 1), a2 + hstepA, voffA);
;             PG8_WAIT_V(8); PG8_WAIT_L(0); PG8_BAR; PG8_MMA(0, 0, At, B0); PG8_MMA(0, 1, At, B1); PG8_BAR; PG8_SCHED;
;             PG8_LDA(At, 1, 1); PG8_STAGE(PG8_SB(1, 0), b3, voffB); PG8_STAGE(PG8_SB(1, 1), b3 + hstepB, voffB); PG8_STAGE(PG8_SA(1, 0), a3, voffA);
;             PG8_WAIT_V(8); PG8_WAIT_L(0); PG8_BAR; PG8_MMA(1, 0, At, B0); PG8_MMA(1, 1, At, B1); PG8_BAR; PG8_SCHED;
;     ...
;         if constexpr (ALIGN_EPI) { if (wr == 0) PG8_BAR; }
;         if constexpr (!Epi::AFTER_DRAIN) { E(acc, cur, wr, wc, fr, fq); S.done(cur); }
;         if (!has_next) break;
	s_nop 4
	ds_read_b128 v[12:15], v218
	ds_read_b128 v[16:19], v218 offset:1024
	ds_read_b128 v[166:169], v218 offset:2048
	ds_read_b128 v[198:201], v218 offset:3072
	ds_read_b128 v[202:205], v226
	ds_read_b128 v[218:221], v226 offset:1024
	ds_read_b128 v[222:225], v226 offset:2048
	ds_read_b128 v[226:229], v226 offset:3072
	s_add_u32 s2, s84, 0x10000
	s_addc_u32 s3, s85, 0
	s_mov_b32 m0, s34
	v_lshl_add_u64 v[52:53], s[2:3], 0, v[132:133]
	ds_read_b128 v[20:23], v137 offset:32768
	ds_read_b128 v[28:31], v137 offset:33792
	ds_read_b128 v[56:59], v137 offset:34816
	ds_read_b128 v[230:233], v137 offset:35840
	ds_read_b128 v[234:237], v137 offset:36864
	ds_read_b128 v[238:241], v137 offset:37888
	ds_read_b128 v[248:251], v137 offset:38912
	ds_read_b128 v[244:247], v137 offset:39936
	global_load_lds_dwordx4 v[52:53], off
	v_lshl_add_u64 v[52:53], s[2:3], 0, v[130:131]
	s_mov_b32 m0, s45
	s_nop 0
	global_load_lds_dwordx4 v[52:53], off
	s_waitcnt vmcnt(8)
	s_waitcnt lgkmcnt(0)
	s_barrier
	s_waitcnt lgkmcnt(0)
	v_mfma_f32_16x16x32_bf16 v[52:55], v[12:15], v[20:23], v[64:67]
	v_mfma_f32_16x16x32_bf16 v[124:127], v[16:19], v[28:31], v[52:55]
	v_mfma_f32_16x16x32_bf16 v[52:55], v[166:169], v[20:23], v[68:71]
	v_mfma_f32_16x16x32_bf16 v[120:123], v[198:201], v[28:31], v[52:55]
	v_mfma_f32_16x16x32_bf16 v[52:55], v[12:15], v[56:59], v[72:75]
	v_mfma_f32_16x16x32_bf16 v[108:111], v[16:19], v[230:233], v[52:55]
	v_mfma_f32_16x16x32_bf16 v[52:55], v[166:169], v[56:59], v[76:79]
	v_mfma_f32_16x16x32_bf16 v[100:103], v[198:201], v[230:233], v[52:55]
	v_mfma_f32_16x16x32_bf16 v[52:55], v[12:15], v[234:237], v[80:83]
	v_mfma_f32_16x16x32_bf16 v[92:95], v[16:19], v[238:241], v[52:55]
	v_mfma_f32_16x16x32_bf16 v[52:55], v[166:169], v[234:237], v[84:87]
	v_mfma_f32_16x16x32_bf16 v[84:87], v[198:201], v[238:241], v[52:55]
	v_mfma_f32_16x16x32_bf16 v[52:55], v[12:15], v[248:251], v[88:91]
	v_mfma_f32_16x16x32_bf16 v[60:63], v[16:19], v[244:247], v[52:55]
	v_mfma_f32_16x16x32_bf16 v[52:55], v[166:169], v[248:251], v[210:213]
	v_mfma_f32_16x16x32_bf16 v[52:55], v[198:201], v[244:247], v[52:55]
	v_mfma_f32_16x16x32_bf16 v[64:67], v[202:205], v[20:23], v[96:99]
	v_mfma_f32_16x16x32_bf16 v[20:23], v[222:225], v[20:23], v[32:35]
	v_mfma_f32_16x16x32_bf16 v[112:115], v[226:229], v[28:31], v[20:23]
	v_mfma_f32_16x16x32_bf16 v[20:23], v[202:205], v[56:59], v[36:39]
	v_mfma_f32_16x16x32_bf16 v[104:107], v[218:221], v[230:233], v[20:23]
	v_mfma_f32_16x16x32_bf16 v[20:23], v[222:225], v[56:59], v[40:43]
	v_mfma_f32_16x16x32_bf16 v[96:99], v[226:229], v[230:233], v[20:23]
	v_mfma_f32_16x16x32_bf16 v[20:23], v[202:205], v[234:237], v[44:47]
	v_mfma_f32_16x16x32_bf16 v[88:91], v[218:221], v[238:241], v[20:23]
	v_mfma_f32_16x16x32_bf16 v[20:23], v[222:225], v[234:237], v[48:51]
	v_mfma_f32_16x16x32_bf16 v[80:83], v[226:229], v[238:241], v[20:23]
	v_mfma_f32_16x16x32_bf16 v[20:23], v[202:205], v[248:251], v[170:173]
	v_mfma_f32_16x16x32_bf16 v[56:59], v[218:221], v[244:247], v[20:23]
	v_mfma_f32_16x16x32_bf16 v[20:23], v[222:225], v[248:251], v[174:177]
	v_mfma_f32_16x16x32_bf16 v[116:119], v[218:221], v[28:31], v[64:67]
	v_mfma_f32_16x16x32_bf16 v[48:51], v[226:229], v[244:247], v[20:23]
	s_barrier
	s_mov_b32 m0, s92
	s_nop 2
	v_lshl_add_u64 v[20:21], v[134:135], 0, s[36:37]
	s_add_u32 s2, s82, 0x10080
	ds_read_b128 v[32:35], v137 offset:49152
	ds_read_b128 v[40:43], v137 offset:50176
	ds_read_b128 v[170:173], v137 offset:51200
	ds_read_b128 v[174:177], v137 offset:52224
	ds_read_b128 v[210:213], v137 offset:53248
	ds_read_b128 v[230:233], v137 offset:54272
	ds_read_b128 v[234:237], v137 offset:55296
	ds_read_b128 v[238:241], v137 offset:56320
	global_load_lds_dwordx4 v[20:21], off
	v_lshl_add_u64 v[20:21], v[190:191], 0, s[36:37]
	s_mov_b32 m0, s90
	s_addc_u32 s3, s83, 0
	global_load_lds_dwordx4 v[20:21], off
	v_lshl_add_u64 v[20:21], s[2:3], 0, v[192:193]
	s_mov_b32 m0, s88
	s_nop 0
	global_load_lds_dwordx4 v[20:21], off
	v_lshl_add_u64 v[20:21], s[2:3], 0, v[128:129]
	s_mov_b32 m0, s89
	s_nop 0
	global_load_lds_dwordx4 v[20:21], off
	v_lshl_add_u64 v[20:21], v[194:195], 0, s[36:37]
	s_mov_b32 m0, s63
	s_nop 0
	global_load_lds_dwordx4 v[20:21], off
	v_lshl_add_u64 v[20:21], v[196:197], 0, s[36:37]
	s_mov_b32 m0, s64
	s_nop 0
	global_load_lds_dwordx4 v[20:21], off
	s_waitcnt vmcnt(8)
	s_waitcnt lgkmcnt(0)
	s_barrier
	s_waitcnt lgkmcnt(0)
	v_mfma_f32_16x16x32_bf16 v[20:23], v[12:15], v[32:35], v[138:141]
	v_mfma_f32_16x16x32_bf16 v[76:79], v[16:19], v[40:43], v[20:23]
	v_mfma_f32_16x16x32_bf16 v[20:23], v[166:169], v[32:35], v[142:145]
	v_mfma_f32_16x16x32_bf16 v[68:71], v[198:201], v[40:43], v[20:23]
	v_mfma_f32_16x16x32_bf16 v[20:23], v[12:15], v[170:173], v[146:149]
	v_mfma_f32_16x16x32_bf16 v[44:47], v[16:19], v[174:177], v[20:23]
	v_mfma_f32_16x16x32_bf16 v[20:23], v[166:169], v[170:173], v[150:153]
	v_mfma_f32_16x16x32_bf16 v[36:39], v[198:201], v[174:177], v[20:23]
	v_mfma_f32_16x16x32_bf16 v[20:23], v[12:15], v[210:213], v[154:157]
	v_mfma_f32_16x16x32_bf16 v[0:3], v[12:15], v[234:237], v[0:3]
	v_mfma_f32_16x16x32_bf16 v[28:31], v[16:19], v[230:233], v[20:23]
	v_mfma_f32_16x16x32_bf16 v[20:23], v[166:169], v[210:213], v[158:161]
	v_mfma_f32_16x16x32_bf16 v[12:15], v[16:19], v[238:241], v[0:3]
	v_mfma_f32_16x16x32_bf16 v[0:3], v[166:169], v[234:237], v[4:7]
	v_mfma_f32_16x16x32_bf16 v[20:23], v[198:201], v[230:233], v[20:23]
	v_mfma_f32_16x16x32_bf16 v[4:7], v[198:201], v[238:241], v[0:3]
	v_mfma_f32_16x16x32_bf16 v[0:3], v[202:205], v[32:35], v[8:11]
	v_mfma_f32_16x16x32_bf16 v[72:75], v[218:221], v[40:43], v[0:3]
	v_mfma_f32_16x16x32_bf16 v[0:3], v[222:225], v[32:35], v[206:209]
	v_mfma_f32_16x16x32_bf16 v[64:67], v[226:229], v[40:43], v[0:3]
	v_mfma_f32_16x16x32_bf16 v[0:3], v[202:205], v[170:173], v[24:27]
	v_mfma_f32_16x16x32_bf16 v[40:43], v[218:221], v[174:177], v[0:3]
	v_mfma_f32_16x16x32_bf16 v[0:3], v[222:225], v[170:173], v[178:181]
	v_mfma_f32_16x16x32_bf16 v[32:35], v[226:229], v[174:177], v[0:3]
	v_mfma_f32_16x16x32_bf16 v[0:3], v[202:205], v[210:213], v[214:217]
	v_mfma_f32_16x16x32_bf16 v[24:27], v[218:221], v[230:233], v[0:3]
	v_mfma_f32_16x16x32_bf16 v[0:3], v[222:225], v[210:213], v[182:185]
	v_mfma_f32_16x16x32_bf16 v[16:19], v[226:229], v[230:233], v[0:3]
	v_mfma_f32_16x16x32_bf16 v[0:3], v[202:205], v[234:237], v[186:189]
	v_mfma_f32_16x16x32_bf16 v[8:11], v[218:221], v[238:241], v[0:3]
	v_mfma_f32_16x16x32_bf16 v[0:3], v[222:225], v[234:237], v[162:165]
	v_mfma_f32_16x16x32_bf16 v[0:3], v[226:229], v[238:241], v[0:3]
	s_barrier
	s_andn2_b64 vcc, exec, s[6:7]
	s_cbranch_vccnz .LBB0_673
	s_barrier
